# residual-GEMM epilogue hand-written in two phases: all x loads + FMAs first (16 loads in flight), then all stores, so no load wait sits behind a store; on top of the ctx-first unit order
# speedup vs baseline: 1.0067x; 1.0003x over previous
.LBB0_293:
	s_ashr_i32 s3, s65, 31
	s_sub_i32 s4, s65, 64
	s_lshr_b32 s24, s65, 4
	s_cmp_gt_i32 s65, 63
	s_cselect_b32 s5, 0, s3
	s_cselect_b32 s4, s4, s65
	s_mulk_i32 s24, 0x4800
	s_waitcnt lgkmcnt(0)
	s_cselect_b32 s3, s15, s91
	s_cselect_b32 s28, s14, s90
	s_cselect_b32 s35, s14, s72
	s_cselect_b32 s42, s15, s73
	s_cselect_b32 s34, 0x12000, s24
	s_lshl_b64 s[4:5], s[4:5], 20
	s_add_u32 s28, s28, s4
	s_addc_u32 s29, s3, s5
	s_add_u32 s4, s35, s4
	s_addc_u32 s5, s42, s5
	s_ashr_i32 s35, s34, 31
	s_lshl_b32 s3, s85, 8
	s_or_b32 s3, s3, s1
	s_lshl_b64 s[34:35], s[34:35], 2
	s_add_u32 s34, s58, s34
	v_lshl_add_u32 v154, v67, 2, s3
	s_addc_u32 s35, s92, s35
	v_ashrrev_i32_e32 v155, 31, v154
	v_lshl_add_u64 v[156:157], v[154:155], 2, s[34:35]
	global_load_dwordx4 v[132:135], v[156:157], off
	global_load_dwordx4 v[136:139], v[156:157], off offset:64
	global_load_dwordx4 v[140:143], v[156:157], off offset:512
	global_load_dwordx4 v[168:171], v[156:157], off offset:576
	v_add_u32_e32 v163, s0, v164
	v_lshlrev_b32_e32 v163, 12, v163
	v_lshl_add_u32 v162, v154, 2, v163
	s_mov_b32 s3, 0
	s_mov_b32 s24, 64
	v_cmp_lt_u32_e32 vcc, 7, v164
	v_mov_b32_e32 v243, s3
	v_cndmask_b32_e32 v243, 0, v243, vcc
	v_mov_b32_e32 v163, s24
	v_cndmask_b32_e64 v163, v163, 64, vcc
	v_add_u32_e32 v163, v162, v163
	v_add_u32_e32 v162, v162, v243
	s_andn2_b64 vcc, exec, s[30:31]
	s_cbranch_vccz .Lepi_r_split
	global_load_dwordx4 v[150:153], v162, s[28:29]
	global_load_dwordx4 v[154:157], v163, s[28:29]
	global_load_dwordx4 v[158:161], v162, s[28:29] offset:512
	global_load_dwordx4 v[244:247], v163, s[28:29] offset:512
	s_add_u32 s28, s28, 0x10000
	s_addc_u32 s29, s29, 0
	global_load_dwordx4 v[248:251], v162, s[28:29]
	global_load_dwordx4 v[252:255], v163, s[28:29]
	global_load_dwordx4 v[172:175], v162, s[28:29] offset:512
	global_load_dwordx4 v[176:179], v163, s[28:29] offset:512
	s_add_u32 s28, s28, 0x10000
	s_addc_u32 s29, s29, 0
	global_load_dwordx4 v[190:193], v162, s[28:29]
	global_load_dwordx4 v[194:197], v163, s[28:29]
	global_load_dwordx4 v[198:201], v162, s[28:29] offset:512
	global_load_dwordx4 v[202:205], v163, s[28:29] offset:512
	s_add_u32 s28, s28, 0x10000
	s_addc_u32 s29, s29, 0
	global_load_dwordx4 v[206:209], v162, s[28:29]
	global_load_dwordx4 v[210:213], v163, s[28:29]
	global_load_dwordx4 v[214:217], v162, s[28:29] offset:512
	global_load_dwordx4 v[228:231], v163, s[28:29] offset:512
	s_waitcnt vmcnt(16)
	v_mul_f32_e32 v132, s88, v132
	v_mul_f32_e32 v133, s88, v133
	v_mul_f32_e32 v134, s88, v134
	v_mul_f32_e32 v135, s88, v135
	v_mul_f32_e32 v136, s88, v136
	v_mul_f32_e32 v137, s88, v137
	v_mul_f32_e32 v138, s88, v138
	v_mul_f32_e32 v139, s88, v139
	v_mul_f32_e32 v140, s88, v140
	v_mul_f32_e32 v141, s88, v141
	v_mul_f32_e32 v142, s88, v142
	v_mul_f32_e32 v143, s88, v143
	v_mul_f32_e32 v168, s88, v168
	v_mul_f32_e32 v169, s88, v169
	v_mul_f32_e32 v170, s88, v170
	v_mul_f32_e32 v171, s88, v171
	s_waitcnt vmcnt(14)
	v_pk_fma_f32 v[128:129], v[128:129], v[132:133], v[150:151]
	v_pk_fma_f32 v[130:131], v[130:131], v[134:135], v[152:153]
	v_pk_fma_f32 v[124:125], v[124:125], v[136:137], v[154:155]
	v_pk_fma_f32 v[126:127], v[126:127], v[138:139], v[156:157]
	s_add_u32 s28, s28, 0x50000
	s_addc_u32 s29, s29, 0
	global_load_dwordx4 v[150:153], v162, s[28:29]
	global_load_dwordx4 v[154:157], v163, s[28:29]
	s_waitcnt vmcnt(14)
	v_pk_fma_f32 v[120:121], v[120:121], v[140:141], v[158:159]
	v_pk_fma_f32 v[122:123], v[122:123], v[142:143], v[160:161]
	v_pk_fma_f32 v[116:117], v[116:117], v[168:169], v[244:245]
	v_pk_fma_f32 v[118:119], v[118:119], v[170:171], v[246:247]
	global_load_dwordx4 v[158:161], v162, s[28:29] offset:512
	global_load_dwordx4 v[244:247], v163, s[28:29] offset:512
	s_waitcnt vmcnt(14)
	v_pk_fma_f32 v[112:113], v[112:113], v[132:133], v[248:249]
	v_pk_fma_f32 v[114:115], v[114:115], v[134:135], v[250:251]
	v_pk_fma_f32 v[108:109], v[108:109], v[136:137], v[252:253]
	v_pk_fma_f32 v[110:111], v[110:111], v[138:139], v[254:255]
	s_add_u32 s28, s28, 0x10000
	s_addc_u32 s29, s29, 0
	global_load_dwordx4 v[248:251], v162, s[28:29]
	global_load_dwordx4 v[252:255], v163, s[28:29]
	s_waitcnt vmcnt(14)
	v_pk_fma_f32 v[104:105], v[104:105], v[140:141], v[172:173]
	v_pk_fma_f32 v[106:107], v[106:107], v[142:143], v[174:175]
	v_pk_fma_f32 v[100:101], v[100:101], v[168:169], v[176:177]
	v_pk_fma_f32 v[102:103], v[102:103], v[170:171], v[178:179]
	global_load_dwordx4 v[172:175], v162, s[28:29] offset:512
	global_load_dwordx4 v[176:179], v163, s[28:29] offset:512
	s_waitcnt vmcnt(14)
	v_pk_fma_f32 v[96:97], v[96:97], v[132:133], v[190:191]
	v_pk_fma_f32 v[98:99], v[98:99], v[134:135], v[192:193]
	v_pk_fma_f32 v[92:93], v[92:93], v[136:137], v[194:195]
	v_pk_fma_f32 v[94:95], v[94:95], v[138:139], v[196:197]
	s_add_u32 s28, s28, 0x10000
	s_addc_u32 s29, s29, 0
	global_load_dwordx4 v[190:193], v162, s[28:29]
	global_load_dwordx4 v[194:197], v163, s[28:29]
	s_waitcnt vmcnt(14)
	v_pk_fma_f32 v[88:89], v[88:89], v[140:141], v[198:199]
	v_pk_fma_f32 v[90:91], v[90:91], v[142:143], v[200:201]
	v_pk_fma_f32 v[84:85], v[84:85], v[168:169], v[202:203]
	v_pk_fma_f32 v[86:87], v[86:87], v[170:171], v[204:205]
	global_load_dwordx4 v[198:201], v162, s[28:29] offset:512
	global_load_dwordx4 v[202:205], v163, s[28:29] offset:512
	s_waitcnt vmcnt(14)
	v_pk_fma_f32 v[80:81], v[80:81], v[132:133], v[206:207]
	v_pk_fma_f32 v[82:83], v[82:83], v[134:135], v[208:209]
	v_pk_fma_f32 v[76:77], v[76:77], v[136:137], v[210:211]
	v_pk_fma_f32 v[78:79], v[78:79], v[138:139], v[212:213]
	s_add_u32 s28, s28, 0x10000
	s_addc_u32 s29, s29, 0
	global_load_dwordx4 v[206:209], v162, s[28:29]
	global_load_dwordx4 v[210:213], v163, s[28:29]
	s_waitcnt vmcnt(14)
	v_pk_fma_f32 v[72:73], v[72:73], v[140:141], v[214:215]
	v_pk_fma_f32 v[74:75], v[74:75], v[142:143], v[216:217]
	v_pk_fma_f32 v[68:69], v[68:69], v[168:169], v[228:229]
	v_pk_fma_f32 v[70:71], v[70:71], v[170:171], v[230:231]
	global_load_dwordx4 v[214:217], v162, s[28:29] offset:512
	global_load_dwordx4 v[228:231], v163, s[28:29] offset:512
	s_waitcnt vmcnt(14)
	v_pk_fma_f32 v[62:63], v[62:63], v[132:133], v[150:151]
	v_pk_fma_f32 v[64:65], v[64:65], v[134:135], v[152:153]
	v_pk_fma_f32 v[58:59], v[58:59], v[136:137], v[154:155]
	v_pk_fma_f32 v[60:61], v[60:61], v[138:139], v[156:157]
	s_waitcnt vmcnt(12)
	v_pk_fma_f32 v[54:55], v[54:55], v[140:141], v[158:159]
	v_pk_fma_f32 v[56:57], v[56:57], v[142:143], v[160:161]
	v_pk_fma_f32 v[50:51], v[50:51], v[168:169], v[244:245]
	v_pk_fma_f32 v[52:53], v[52:53], v[170:171], v[246:247]
	s_waitcnt vmcnt(10)
	v_pk_fma_f32 v[46:47], v[46:47], v[132:133], v[248:249]
	v_pk_fma_f32 v[48:49], v[48:49], v[134:135], v[250:251]
	v_pk_fma_f32 v[42:43], v[42:43], v[136:137], v[252:253]
	v_pk_fma_f32 v[44:45], v[44:45], v[138:139], v[254:255]
	s_waitcnt vmcnt(8)
	v_pk_fma_f32 v[38:39], v[38:39], v[140:141], v[172:173]
	v_pk_fma_f32 v[40:41], v[40:41], v[142:143], v[174:175]
	v_pk_fma_f32 v[34:35], v[34:35], v[168:169], v[176:177]
	v_pk_fma_f32 v[36:37], v[36:37], v[170:171], v[178:179]
	s_waitcnt vmcnt(6)
	v_pk_fma_f32 v[30:31], v[30:31], v[132:133], v[190:191]
	v_pk_fma_f32 v[32:33], v[32:33], v[134:135], v[192:193]
	v_pk_fma_f32 v[26:27], v[26:27], v[136:137], v[194:195]
	v_pk_fma_f32 v[28:29], v[28:29], v[138:139], v[196:197]
	s_waitcnt vmcnt(4)
	v_pk_fma_f32 v[22:23], v[22:23], v[140:141], v[198:199]
	v_pk_fma_f32 v[24:25], v[24:25], v[142:143], v[200:201]
	v_pk_fma_f32 v[18:19], v[18:19], v[168:169], v[202:203]
	v_pk_fma_f32 v[20:21], v[20:21], v[170:171], v[204:205]
	s_waitcnt vmcnt(2)
	v_pk_fma_f32 v[14:15], v[14:15], v[132:133], v[206:207]
	v_pk_fma_f32 v[16:17], v[16:17], v[134:135], v[208:209]
	v_pk_fma_f32 v[10:11], v[10:11], v[136:137], v[210:211]
	v_pk_fma_f32 v[12:13], v[12:13], v[138:139], v[212:213]
	s_waitcnt vmcnt(0)
	v_pk_fma_f32 v[6:7], v[6:7], v[140:141], v[214:215]
	v_pk_fma_f32 v[8:9], v[8:9], v[142:143], v[216:217]
	v_pk_fma_f32 v[2:3], v[2:3], v[168:169], v[228:229]
	v_pk_fma_f32 v[4:5], v[4:5], v[170:171], v[230:231]
	global_store_dwordx4 v162, v[128:131], s[4:5]
	global_store_dwordx4 v163, v[124:127], s[4:5]
	global_store_dwordx4 v162, v[120:123], s[4:5] offset:512
	global_store_dwordx4 v163, v[116:119], s[4:5] offset:512
	s_add_u32 s4, s4, 0x10000
	s_addc_u32 s5, s5, 0
	global_store_dwordx4 v162, v[112:115], s[4:5]
	global_store_dwordx4 v163, v[108:111], s[4:5]
	global_store_dwordx4 v162, v[104:107], s[4:5] offset:512
	global_store_dwordx4 v163, v[100:103], s[4:5] offset:512
	s_add_u32 s4, s4, 0x10000
	s_addc_u32 s5, s5, 0
	global_store_dwordx4 v162, v[96:99], s[4:5]
	global_store_dwordx4 v163, v[92:95], s[4:5]
	global_store_dwordx4 v162, v[88:91], s[4:5] offset:512
	global_store_dwordx4 v163, v[84:87], s[4:5] offset:512
	s_add_u32 s4, s4, 0x10000
	s_addc_u32 s5, s5, 0
	global_store_dwordx4 v162, v[80:83], s[4:5]
	global_store_dwordx4 v163, v[76:79], s[4:5]
	global_store_dwordx4 v162, v[72:75], s[4:5] offset:512
	global_store_dwordx4 v163, v[68:71], s[4:5] offset:512
	s_add_u32 s4, s4, 0x50000
	s_addc_u32 s5, s5, 0
	global_store_dwordx4 v162, v[62:65], s[4:5]
	global_store_dwordx4 v163, v[58:61], s[4:5]
	global_store_dwordx4 v162, v[54:57], s[4:5] offset:512
	global_store_dwordx4 v163, v[50:53], s[4:5] offset:512
	s_add_u32 s4, s4, 0x10000
	s_addc_u32 s5, s5, 0
	global_store_dwordx4 v162, v[46:49], s[4:5]
	global_store_dwordx4 v163, v[42:45], s[4:5]
	global_store_dwordx4 v162, v[38:41], s[4:5] offset:512
	global_store_dwordx4 v163, v[34:37], s[4:5] offset:512
	s_add_u32 s4, s4, 0x10000
	s_addc_u32 s5, s5, 0
	global_store_dwordx4 v162, v[30:33], s[4:5]
	global_store_dwordx4 v163, v[26:29], s[4:5]
	global_store_dwordx4 v162, v[22:25], s[4:5] offset:512
	global_store_dwordx4 v163, v[18:21], s[4:5] offset:512
	s_add_u32 s4, s4, 0x10000
	s_addc_u32 s5, s5, 0
	global_store_dwordx4 v162, v[14:17], s[4:5]
	global_store_dwordx4 v163, v[10:13], s[4:5]
	global_store_dwordx4 v162, v[6:9], s[4:5] offset:512
	global_store_dwordx4 v163, v[2:5], s[4:5] offset:512
	s_branch .Lepi_r_done
.Lepi_r_split:
	s_lshl_b32 s3, s65, 8
	s_ashr_i32 s85, s84, 31
	s_add_i32 s30, s3, 0xffffc000
	s_ashr_i32 s31, s30, 31
	s_lshl_b64 s[34:35], s[84:85], 22
	s_add_u32 s3, s93, s34
	s_addc_u32 s24, s53, s35
	s_lshl_b64 s[30:31], s[30:31], 12
	s_add_u32 s30, s3, s30
	s_addc_u32 s31, s24, s31
	s_waitcnt vmcnt(0)
	v_mul_f32_e32 v132, s88, v132
	v_mul_f32_e32 v133, s88, v133
	v_mul_f32_e32 v134, s88, v134
	v_mul_f32_e32 v135, s88, v135
	v_mul_f32_e32 v136, s88, v136
	v_mul_f32_e32 v137, s88, v137
	v_mul_f32_e32 v138, s88, v138
	v_mul_f32_e32 v139, s88, v139
	v_mul_f32_e32 v140, s88, v140
	v_mul_f32_e32 v141, s88, v141
	v_mul_f32_e32 v142, s88, v142
	v_mul_f32_e32 v143, s88, v143
	v_mul_f32_e32 v168, s88, v168
	v_mul_f32_e32 v169, s88, v169
	v_mul_f32_e32 v170, s88, v170
	v_mul_f32_e32 v171, s88, v171
	v_pk_mul_f32 v[150:151], v[132:133], v[128:129]
	v_pk_mul_f32 v[152:153], v[134:135], v[130:131]
	global_store_dwordx4 v162, v[150:153], s[30:31]
	v_pk_mul_f32 v[154:155], v[136:137], v[124:125]
	v_pk_mul_f32 v[156:157], v[138:139], v[126:127]
	global_store_dwordx4 v163, v[154:157], s[30:31]
	v_pk_mul_f32 v[158:159], v[140:141], v[120:121]
	v_pk_mul_f32 v[160:161], v[142:143], v[122:123]
	global_store_dwordx4 v162, v[158:161], s[30:31] offset:512
	v_pk_mul_f32 v[244:245], v[168:169], v[116:117]
	v_pk_mul_f32 v[246:247], v[170:171], v[118:119]
	global_store_dwordx4 v163, v[244:247], s[30:31] offset:512
	s_add_u32 s30, s30, 0x10000
	s_addc_u32 s31, s31, 0
	v_pk_mul_f32 v[248:249], v[132:133], v[112:113]
	v_pk_mul_f32 v[250:251], v[134:135], v[114:115]
	global_store_dwordx4 v162, v[248:251], s[30:31]
	v_pk_mul_f32 v[252:253], v[136:137], v[108:109]
	v_pk_mul_f32 v[254:255], v[138:139], v[110:111]
	global_store_dwordx4 v163, v[252:255], s[30:31]
	v_pk_mul_f32 v[150:151], v[140:141], v[104:105]
	v_pk_mul_f32 v[152:153], v[142:143], v[106:107]
	global_store_dwordx4 v162, v[150:153], s[30:31] offset:512
	v_pk_mul_f32 v[154:155], v[168:169], v[100:101]
	v_pk_mul_f32 v[156:157], v[170:171], v[102:103]
	global_store_dwordx4 v163, v[154:157], s[30:31] offset:512
	s_add_u32 s30, s30, 0x10000
	s_addc_u32 s31, s31, 0
	v_pk_mul_f32 v[158:159], v[132:133], v[96:97]
	v_pk_mul_f32 v[160:161], v[134:135], v[98:99]
	global_store_dwordx4 v162, v[158:161], s[30:31]
	v_pk_mul_f32 v[244:245], v[136:137], v[92:93]
	v_pk_mul_f32 v[246:247], v[138:139], v[94:95]
	global_store_dwordx4 v163, v[244:247], s[30:31]
	v_pk_mul_f32 v[248:249], v[140:141], v[88:89]
	v_pk_mul_f32 v[250:251], v[142:143], v[90:91]
	global_store_dwordx4 v162, v[248:251], s[30:31] offset:512
	v_pk_mul_f32 v[252:253], v[168:169], v[84:85]
	v_pk_mul_f32 v[254:255], v[170:171], v[86:87]
	global_store_dwordx4 v163, v[252:255], s[30:31] offset:512
	s_add_u32 s30, s30, 0x10000
	s_addc_u32 s31, s31, 0
	v_pk_mul_f32 v[150:151], v[132:133], v[80:81]
	v_pk_mul_f32 v[152:153], v[134:135], v[82:83]
	global_store_dwordx4 v162, v[150:153], s[30:31]
	v_pk_mul_f32 v[154:155], v[136:137], v[76:77]
	v_pk_mul_f32 v[156:157], v[138:139], v[78:79]
	global_store_dwordx4 v163, v[154:157], s[30:31]
	v_pk_mul_f32 v[158:159], v[140:141], v[72:73]
	v_pk_mul_f32 v[160:161], v[142:143], v[74:75]
	global_store_dwordx4 v162, v[158:161], s[30:31] offset:512
	v_pk_mul_f32 v[244:245], v[168:169], v[68:69]
	v_pk_mul_f32 v[246:247], v[170:171], v[70:71]
	global_store_dwordx4 v163, v[244:247], s[30:31] offset:512
	s_add_u32 s30, s30, 0x50000
	s_addc_u32 s31, s31, 0
	v_pk_mul_f32 v[248:249], v[132:133], v[62:63]
	v_pk_mul_f32 v[250:251], v[134:135], v[64:65]
	global_store_dwordx4 v162, v[248:251], s[30:31]
	v_pk_mul_f32 v[252:253], v[136:137], v[58:59]
	v_pk_mul_f32 v[254:255], v[138:139], v[60:61]
	global_store_dwordx4 v163, v[252:255], s[30:31]
	v_pk_mul_f32 v[150:151], v[140:141], v[54:55]
	v_pk_mul_f32 v[152:153], v[142:143], v[56:57]
	global_store_dwordx4 v162, v[150:153], s[30:31] offset:512
	v_pk_mul_f32 v[154:155], v[168:169], v[50:51]
	v_pk_mul_f32 v[156:157], v[170:171], v[52:53]
	global_store_dwordx4 v163, v[154:157], s[30:31] offset:512
	s_add_u32 s30, s30, 0x10000
	s_addc_u32 s31, s31, 0
	v_pk_mul_f32 v[158:159], v[132:133], v[46:47]
	v_pk_mul_f32 v[160:161], v[134:135], v[48:49]
	global_store_dwordx4 v162, v[158:161], s[30:31]
	v_pk_mul_f32 v[244:245], v[136:137], v[42:43]
	v_pk_mul_f32 v[246:247], v[138:139], v[44:45]
	global_store_dwordx4 v163, v[244:247], s[30:31]
	v_pk_mul_f32 v[248:249], v[140:141], v[38:39]
	v_pk_mul_f32 v[250:251], v[142:143], v[40:41]
	global_store_dwordx4 v162, v[248:251], s[30:31] offset:512
	v_pk_mul_f32 v[252:253], v[168:169], v[34:35]
	v_pk_mul_f32 v[254:255], v[170:171], v[36:37]
	global_store_dwordx4 v163, v[252:255], s[30:31] offset:512
	s_add_u32 s30, s30, 0x10000
	s_addc_u32 s31, s31, 0
	v_pk_mul_f32 v[150:151], v[132:133], v[30:31]
	v_pk_mul_f32 v[152:153], v[134:135], v[32:33]
	global_store_dwordx4 v162, v[150:153], s[30:31]
	v_pk_mul_f32 v[154:155], v[136:137], v[26:27]
	v_pk_mul_f32 v[156:157], v[138:139], v[28:29]
	global_store_dwordx4 v163, v[154:157], s[30:31]
	v_pk_mul_f32 v[158:159], v[140:141], v[22:23]
	v_pk_mul_f32 v[160:161], v[142:143], v[24:25]
	global_store_dwordx4 v162, v[158:161], s[30:31] offset:512
	v_pk_mul_f32 v[244:245], v[168:169], v[18:19]
	v_pk_mul_f32 v[246:247], v[170:171], v[20:21]
	global_store_dwordx4 v163, v[244:247], s[30:31] offset:512
	s_add_u32 s30, s30, 0x10000
	s_addc_u32 s31, s31, 0
	v_pk_mul_f32 v[248:249], v[132:133], v[14:15]
	v_pk_mul_f32 v[250:251], v[134:135], v[16:17]
	global_store_dwordx4 v162, v[248:251], s[30:31]
	v_pk_mul_f32 v[252:253], v[136:137], v[10:11]
	v_pk_mul_f32 v[254:255], v[138:139], v[12:13]
	global_store_dwordx4 v163, v[252:255], s[30:31]
	v_pk_mul_f32 v[150:151], v[140:141], v[6:7]
	v_pk_mul_f32 v[152:153], v[142:143], v[8:9]
	global_store_dwordx4 v162, v[150:153], s[30:31] offset:512
	v_pk_mul_f32 v[154:155], v[168:169], v[2:3]
	v_pk_mul_f32 v[156:157], v[170:171], v[4:5]
	global_store_dwordx4 v163, v[154:157], s[30:31] offset:512
